# GEMM K-loop: last 2 of the 6 LDS-DMA loads of each SP2 load segment moved into the following MFMA segment (after MFMA 4 and 12); that segment's wait counted down vmcnt(8)->(6)
# baseline (speedup 1.0000x reference)
; #define PG8_STAGE(bufoff, gbase, voff) do { _Pragma("unroll") for (int _i = 0; _i < 2; ++_i) \
;         __builtin_amdgcn_global_load_lds((const unsigned*)((const char*)(gbase) + (voff)[_i]), (PG8_LAS unsigned*)(lds + (bufoff) + ldsw + _i * 8192), 16, 0, 0); } while (0)
; #define PG8_LDA(dst, b, h) do { _Pragma("unroll") for (int m = 0; m < 4; ++m) _Pragma("unroll") for (int k = 0; k < 2; ++k) dst[m][k] = *(const PG8_LAS bf16x8*)(lds + PG8_SA(b, h) + aoff + m * 2048 + k * 1024); } while (0)
; #define PG8_LDB(dst, b, h) do { _Pragma("unroll") for (int n = 0; n < 2; ++n) _Pragma("unroll") for (int k = 0; k < 2; ++k) dst[n][k] = *(const PG8_LAS bf16x8*)(lds + PG8_SB(b, h) + boff + n * 2048 + k * 1024); } while (0)
; #define PG8_MMA(ai, bj, At, Bt) do { __builtin_amdgcn_s_setprio(1); _Pragma("unroll") for (int m = 0; m < 4; ++m) _Pragma("unroll") for (int n = 0; n < 2; ++n) _Pragma("unroll") for (int k = 0; k < 2; ++k) \
;         acc[ai][bj][m][n] = __builtin_amdgcn_mfma_f32_16x16x32_bf16(Bt[n][k], At[m][k], acc[ai][bj][m][n], 0, 0, 0); __builtin_amdgcn_s_setprio(0); } while (0)
; #define PG8_WAIT_V(n) asm volatile("s_waitcnt vmcnt(" #n ")" ::: "memory")
; #define PG8_WAIT_L(n) asm volatile("s_waitcnt lgkmcnt(" #n ")" ::: "memory")
; #define PG8_BAR __builtin_amdgcn_s_barrier()
; #define PG8_SCHED __builtin_amdgcn_sched_barrier(0)
; template <class Epi, class Sched, bool ALIGN_EPI = false, bool SP2 = false>
; __device__ __forceinline__ void gemm_phase(PG8_LAS unsigned char* lds, const Gemm g, const Sched& S, const Epi& E) {
;     ...
;             PG8_LDB(B0, 0, 0); PG8_LDB(B1, 0, 1); PG8_SCHED; PG8_LDA(At, 0, 0); PG8_STAGE(PG8_SA(1, 1), a1 + hstep, voffA);
;             PG8_WAIT_V(8); PG8_WAIT_L(0); PG8_BAR; PG8_MMA(0, 0, At, B0); PG8_MMA(0, 1, At, B1); PG8_BAR; PG8_SCHED;
;             PG8_LDA(At, 0, 1); PG8_STAGE(PG8_SB(0, 0), b2, voffB); PG8_STAGE(PG8_SB(0, 1), b2 + hstep, voffB); PG8_STAGE(PG8_SA(0, 0), a2, voffA);
.LBB0_417:
	s_add_u32 s0, s40, 0xfff80080
	s_addc_u32 s1, s41, -1
	s_add_i32 s30, 0, 0x10000
	s_cmp_eq_u32 s19, 28
	s_cselect_b32 s5, s7, s1
	s_cselect_b32 s4, s8, s0
	s_cselect_b32 s1, s9, s17
	s_cselect_b32 s0, s14, s15
	s_add_i32 s33, 0, 0x14000
	v_add_u32_e32 v142, s30, v203
	v_add_u32_e32 v158, s33, v203
	ds_read_b128 v[130:133], v142
	ds_read_b128 v[134:137], v142 offset:1024
	ds_read_b128 v[138:141], v142 offset:2048
	ds_read_b128 v[142:145], v142 offset:3072
	ds_read_b128 v[146:149], v158
	ds_read_b128 v[150:153], v158 offset:1024
	ds_read_b128 v[154:157], v158 offset:2048
	ds_read_b128 v[158:161], v158 offset:3072
	v_lshl_add_u64 v[190:191], s[40:41], 0, v[188:189]
	s_add_i32 m0, s67, 0xc000
	ds_read_b128 v[162:165], v209
	ds_read_b128 v[166:169], v209 offset:1024
	ds_read_b128 v[170:173], v209 offset:2048
	ds_read_b128 v[174:177], v209 offset:3072
	ds_read_b128 v[210:213], v209 offset:4096
	ds_read_b128 v[232:235], v209 offset:5120
	ds_read_b128 v[242:245], v209 offset:6144
	ds_read_b128 v[246:249], v209 offset:7168
	global_load_lds_dwordx4 v[190:191], off
	v_lshl_add_u64 v[190:191], s[40:41], 0, v[186:187]
	s_add_i32 m0, s67, 0xe000
	s_nop 0
	global_load_lds_dwordx4 v[190:191], off
	s_waitcnt vmcnt(8)
	s_waitcnt lgkmcnt(0)
	s_barrier
	s_setprio 1
	s_waitcnt lgkmcnt(0)
	v_mfma_f32_16x16x32_bf16 v[126:129], v[130:133], v[162:165], v[126:129]
	v_mfma_f32_16x16x32_bf16 v[122:125], v[138:141], v[162:165], v[122:125]
	v_mfma_f32_16x16x32_bf16 v[110:113], v[130:133], v[170:173], v[110:113]
	v_mfma_f32_16x16x32_bf16 v[106:109], v[138:141], v[170:173], v[106:109]
	v_mfma_f32_16x16x32_bf16 v[92:95], v[130:133], v[210:213], v[92:95]
	v_mfma_f32_16x16x32_bf16 v[88:91], v[138:141], v[210:213], v[88:91]
	v_mfma_f32_16x16x32_bf16 v[76:79], v[130:133], v[242:245], v[76:79]
	v_mfma_f32_16x16x32_bf16 v[72:75], v[138:141], v[242:245], v[72:75]
	v_mfma_f32_16x16x32_bf16 v[126:129], v[134:137], v[166:169], v[126:129]
	v_mfma_f32_16x16x32_bf16 v[122:125], v[142:145], v[166:169], v[122:125]
	v_mfma_f32_16x16x32_bf16 v[110:113], v[134:137], v[174:177], v[110:113]
	v_mfma_f32_16x16x32_bf16 v[106:109], v[142:145], v[174:177], v[106:109]
	v_mfma_f32_16x16x32_bf16 v[92:95], v[134:137], v[232:235], v[92:95]
	v_mfma_f32_16x16x32_bf16 v[88:91], v[142:145], v[232:235], v[88:91]
	v_mfma_f32_16x16x32_bf16 v[76:79], v[134:137], v[246:249], v[76:79]
	v_mfma_f32_16x16x32_bf16 v[72:75], v[142:145], v[246:249], v[72:75]
	s_setprio 0
	s_setprio 1
	v_mfma_f32_16x16x32_bf16 v[118:121], v[146:149], v[162:165], v[118:121]
	v_mfma_f32_16x16x32_bf16 v[114:117], v[154:157], v[162:165], v[114:117]
	v_mfma_f32_16x16x32_bf16 v[102:105], v[146:149], v[170:173], v[102:105]
	v_mfma_f32_16x16x32_bf16 v[98:101], v[154:157], v[170:173], v[98:101]
	v_mfma_f32_16x16x32_bf16 v[84:87], v[146:149], v[210:213], v[84:87]
	v_mfma_f32_16x16x32_bf16 v[80:83], v[154:157], v[210:213], v[80:83]
	v_mfma_f32_16x16x32_bf16 v[68:71], v[146:149], v[242:245], v[68:71]
	v_mfma_f32_16x16x32_bf16 v[64:67], v[154:157], v[242:245], v[64:67]
	v_mfma_f32_16x16x32_bf16 v[118:121], v[150:153], v[166:169], v[118:121]
	v_mfma_f32_16x16x32_bf16 v[114:117], v[158:161], v[166:169], v[114:117]
	v_mfma_f32_16x16x32_bf16 v[102:105], v[150:153], v[174:177], v[102:105]
	v_mfma_f32_16x16x32_bf16 v[98:101], v[158:161], v[174:177], v[98:101]
	v_mfma_f32_16x16x32_bf16 v[84:87], v[150:153], v[232:235], v[84:87]
	v_mfma_f32_16x16x32_bf16 v[80:83], v[158:161], v[232:235], v[80:83]
	v_mfma_f32_16x16x32_bf16 v[68:71], v[150:153], v[246:249], v[68:71]
	v_mfma_f32_16x16x32_bf16 v[64:67], v[158:161], v[246:249], v[64:67]
	s_setprio 0
	s_barrier
	s_add_i32 s30, s30, s28
	v_lshl_add_u64 v[190:191], s[0:1], 0, v[96:97]
	s_mov_b32 m0, s30
	ds_read_b128 v[162:165], v209 offset:16384
	ds_read_b128 v[166:169], v209 offset:17408
	ds_read_b128 v[170:173], v209 offset:18432
	ds_read_b128 v[174:177], v209 offset:19456
	ds_read_b128 v[210:213], v209 offset:20480
	ds_read_b128 v[232:235], v209 offset:21504
	ds_read_b128 v[242:245], v209 offset:22528
	ds_read_b128 v[246:249], v209 offset:23552
	global_load_lds_dwordx4 v[190:191], off
	s_add_i32 m0, s30, 0x2000
	s_add_u32 s30, s0, 0x80000
	v_lshl_add_u64 v[204:205], s[0:1], 0, v[178:179]
	s_addc_u32 s31, s1, 0
	s_add_i32 s33, s33, s28
	global_load_lds_dwordx4 v[204:205], off
	v_lshl_add_u64 v[214:215], s[30:31], 0, v[96:97]
	s_mov_b32 m0, s33
	v_lshl_add_u64 v[228:229], s[4:5], 0, v[180:181]
	global_load_lds_dwordx4 v[214:215], off
	v_lshl_add_u64 v[214:215], s[30:31], 0, v[178:179]
	s_add_i32 m0, s33, 0x2000
	s_nop 0
	global_load_lds_dwordx4 v[214:215], off
	s_waitcnt vmcnt(6)
	s_waitcnt lgkmcnt(0)
	s_barrier
; #define PG8_STAGE(bufoff, gbase, voff) do { _Pragma("unroll") for (int _i = 0; _i < 2; ++_i) \
;         __builtin_amdgcn_global_load_lds((const unsigned*)((const char*)(gbase) + (voff)[_i]), (PG8_LAS unsigned*)(lds + (bufoff) + ldsw + _i * 8192), 16, 0, 0); } while (0)
; #define PG8_LDA(dst, b, h) do { _Pragma("unroll") for (int m = 0; m < 4; ++m) _Pragma("unroll") for (int k = 0; k < 2; ++k) dst[m][k] = *(const PG8_LAS bf16x8*)(lds + PG8_SA(b, h) + aoff + m * 2048 + k * 1024); } while (0)
; #define PG8_LDB(dst, b, h) do { _Pragma("unroll") for (int n = 0; n < 2; ++n) _Pragma("unroll") for (int k = 0; k < 2; ++k) dst[n][k] = *(const PG8_LAS bf16x8*)(lds + PG8_SB(b, h) + boff + n * 2048 + k * 1024); } while (0)
; #define PG8_MMA(ai, bj, At, Bt) do { __builtin_amdgcn_s_setprio(1); _Pragma("unroll") for (int m = 0; m < 4; ++m) _Pragma("unroll") for (int n = 0; n < 2; ++n) _Pragma("unroll") for (int k = 0; k < 2; ++k) \
;         acc[ai][bj][m][n] = __builtin_amdgcn_mfma_f32_16x16x32_bf16(Bt[n][k], At[m][k], acc[ai][bj][m][n], 0, 0, 0); __builtin_amdgcn_s_setprio(0); } while (0)
; #define PG8_WAIT_V(n) asm volatile("s_waitcnt vmcnt(" #n ")" ::: "memory")
; #define PG8_WAIT_L(n) asm volatile("s_waitcnt lgkmcnt(" #n ")" ::: "memory")
; #define PG8_BAR __builtin_amdgcn_s_barrier()
; #define PG8_SCHED __builtin_amdgcn_sched_barrier(0)
; template <class Epi, class Sched, bool ALIGN_EPI = false, bool SP2 = false>
; __device__ __forceinline__ void gemm_phase(PG8_LAS unsigned char* lds, const Gemm g, const Sched& S, const Epi& E) {
;     ...
;             PG8_WAIT_V(8); PG8_WAIT_L(0); PG8_BAR; PG8_MMA(1, 0, At, B0); PG8_MMA(1, 1, At, B1); PG8_BAR; PG8_SCHED;
;             PG8_LDB(B0, 1, 0); PG8_LDB(B1, 1, 1); PG8_SCHED; PG8_LDA(At, 1, 0); PG8_STAGE(PG8_SA(0, 1), a2 + hstep, voffA);
;             PG8_WAIT_V(8); PG8_WAIT_L(0); PG8_BAR; PG8_MMA(0, 0, At, B0); PG8_MMA(0, 1, At, B1); PG8_BAR; PG8_SCHED;
	s_setprio 1
	s_waitcnt lgkmcnt(0)
	v_mfma_f32_16x16x32_bf16 v[60:63], v[130:133], v[162:165], v[60:63]
	v_mfma_f32_16x16x32_bf16 v[56:59], v[138:141], v[162:165], v[56:59]
	v_mfma_f32_16x16x32_bf16 v[44:47], v[130:133], v[170:173], v[44:47]
	v_mfma_f32_16x16x32_bf16 v[40:43], v[138:141], v[170:173], v[40:43]
	v_lshl_add_u64 v[214:215], s[4:5], 0, v[182:183]
	s_mov_b32 m0, s67
	s_nop 0
	global_load_lds_dwordx4 v[214:215], off
	v_mfma_f32_16x16x32_bf16 v[28:31], v[130:133], v[210:213], v[28:31]
	v_mfma_f32_16x16x32_bf16 v[24:27], v[138:141], v[210:213], v[24:27]
	v_mfma_f32_16x16x32_bf16 v[12:15], v[130:133], v[242:245], v[12:15]
	v_mfma_f32_16x16x32_bf16 v[8:11], v[138:141], v[242:245], v[8:11]
	v_mfma_f32_16x16x32_bf16 v[60:63], v[134:137], v[166:169], v[60:63]
	v_mfma_f32_16x16x32_bf16 v[56:59], v[142:145], v[166:169], v[56:59]
	v_mfma_f32_16x16x32_bf16 v[44:47], v[134:137], v[174:177], v[44:47]
	v_mfma_f32_16x16x32_bf16 v[40:43], v[142:145], v[174:177], v[40:43]
	s_mov_b32 m0, s68
	s_nop 0
	global_load_lds_dwordx4 v[228:229], off
	v_mfma_f32_16x16x32_bf16 v[28:31], v[134:137], v[232:235], v[28:31]
	v_mfma_f32_16x16x32_bf16 v[24:27], v[142:145], v[232:235], v[24:27]
	v_mfma_f32_16x16x32_bf16 v[12:15], v[134:137], v[246:249], v[12:15]
	v_mfma_f32_16x16x32_bf16 v[8:11], v[142:145], v[246:249], v[8:11]
	s_setprio 0
	s_setprio 1
	v_mfma_f32_16x16x32_bf16 v[52:55], v[146:149], v[162:165], v[52:55]
	v_mfma_f32_16x16x32_bf16 v[48:51], v[154:157], v[162:165], v[48:51]
	v_mfma_f32_16x16x32_bf16 v[36:39], v[146:149], v[170:173], v[36:39]
	v_mfma_f32_16x16x32_bf16 v[32:35], v[154:157], v[170:173], v[32:35]
	v_mfma_f32_16x16x32_bf16 v[20:23], v[146:149], v[210:213], v[20:23]
	v_mfma_f32_16x16x32_bf16 v[16:19], v[154:157], v[210:213], v[16:19]
	v_mfma_f32_16x16x32_bf16 v[4:7], v[146:149], v[242:245], v[4:7]
	v_mfma_f32_16x16x32_bf16 v[0:3], v[154:157], v[242:245], v[0:3]
	v_mfma_f32_16x16x32_bf16 v[52:55], v[150:153], v[166:169], v[52:55]
	v_mfma_f32_16x16x32_bf16 v[48:51], v[158:161], v[166:169], v[48:51]
	v_mfma_f32_16x16x32_bf16 v[36:39], v[150:153], v[174:177], v[36:39]
	v_mfma_f32_16x16x32_bf16 v[32:35], v[158:161], v[174:177], v[32:35]
	v_mfma_f32_16x16x32_bf16 v[20:23], v[150:153], v[232:235], v[20:23]
	v_mfma_f32_16x16x32_bf16 v[16:19], v[158:161], v[232:235], v[16:19]
	v_mfma_f32_16x16x32_bf16 v[4:7], v[150:153], v[246:249], v[4:7]
	v_mfma_f32_16x16x32_bf16 v[0:3], v[158:161], v[246:249], v[0:3]
	s_setprio 0
	s_barrier
	s_add_i32 s30, 0, 0x18000
	s_add_i32 s31, 0, 0x1c000
	v_add_u32_e32 v142, s30, v203
	v_add_u32_e32 v158, s31, v203
	ds_read_b128 v[130:133], v142
	ds_read_b128 v[134:137], v142 offset:1024
	ds_read_b128 v[138:141], v142 offset:2048
	ds_read_b128 v[142:145], v142 offset:3072
	ds_read_b128 v[146:149], v158
	ds_read_b128 v[150:153], v158 offset:1024
	ds_read_b128 v[154:157], v158 offset:2048
	ds_read_b128 v[158:161], v158 offset:3072
	s_add_u32 s4, s4, 0x80000
	s_addc_u32 s5, s5, 0
	s_mov_b32 m0, s69
	v_lshl_add_u64 v[230:231], s[4:5], 0, v[182:183]
	ds_read_b128 v[162:165], v209 offset:32768
	ds_read_b128 v[166:169], v209 offset:33792
	ds_read_b128 v[170:173], v209 offset:34816
	ds_read_b128 v[174:177], v209 offset:35840
	ds_read_b128 v[210:213], v209 offset:36864
	ds_read_b128 v[232:235], v209 offset:37888
	ds_read_b128 v[242:245], v209 offset:38912
	ds_read_b128 v[246:249], v209 offset:39936
	global_load_lds_dwordx4 v[230:231], off
	v_lshl_add_u64 v[230:231], s[4:5], 0, v[180:181]
	s_mov_b32 m0, s72
	s_nop 0
	global_load_lds_dwordx4 v[230:231], off
	s_waitcnt vmcnt(8)
	s_waitcnt lgkmcnt(0)
	s_barrier
	s_setprio 1
	s_waitcnt lgkmcnt(0)
	v_mfma_f32_16x16x32_bf16 v[126:129], v[130:133], v[162:165], v[126:129]
	v_mfma_f32_16x16x32_bf16 v[122:125], v[138:141], v[162:165], v[122:125]
	v_mfma_f32_16x16x32_bf16 v[110:113], v[130:133], v[170:173], v[110:113]
	v_mfma_f32_16x16x32_bf16 v[106:109], v[138:141], v[170:173], v[106:109]
	v_mfma_f32_16x16x32_bf16 v[92:95], v[130:133], v[210:213], v[92:95]
	v_mfma_f32_16x16x32_bf16 v[88:91], v[138:141], v[210:213], v[88:91]
	v_mfma_f32_16x16x32_bf16 v[76:79], v[130:133], v[242:245], v[76:79]
	v_mfma_f32_16x16x32_bf16 v[72:75], v[138:141], v[242:245], v[72:75]
	v_mfma_f32_16x16x32_bf16 v[126:129], v[134:137], v[166:169], v[126:129]
	v_mfma_f32_16x16x32_bf16 v[122:125], v[142:145], v[166:169], v[122:125]
	v_mfma_f32_16x16x32_bf16 v[110:113], v[134:137], v[174:177], v[110:113]
	v_mfma_f32_16x16x32_bf16 v[106:109], v[142:145], v[174:177], v[106:109]
	v_mfma_f32_16x16x32_bf16 v[92:95], v[134:137], v[232:235], v[92:95]
	v_mfma_f32_16x16x32_bf16 v[88:91], v[142:145], v[232:235], v[88:91]
	v_mfma_f32_16x16x32_bf16 v[76:79], v[134:137], v[246:249], v[76:79]
	v_mfma_f32_16x16x32_bf16 v[72:75], v[142:145], v[246:249], v[72:75]
	s_setprio 0
	s_setprio 1
	v_mfma_f32_16x16x32_bf16 v[118:121], v[146:149], v[162:165], v[118:121]
	v_mfma_f32_16x16x32_bf16 v[114:117], v[154:157], v[162:165], v[114:117]
	v_mfma_f32_16x16x32_bf16 v[102:105], v[146:149], v[170:173], v[102:105]
	v_mfma_f32_16x16x32_bf16 v[98:101], v[154:157], v[170:173], v[98:101]
	v_mfma_f32_16x16x32_bf16 v[84:87], v[146:149], v[210:213], v[84:87]
	v_mfma_f32_16x16x32_bf16 v[80:83], v[154:157], v[210:213], v[80:83]
	v_mfma_f32_16x16x32_bf16 v[68:71], v[146:149], v[242:245], v[68:71]
	v_mfma_f32_16x16x32_bf16 v[64:67], v[154:157], v[242:245], v[64:67]
	v_mfma_f32_16x16x32_bf16 v[118:121], v[150:153], v[166:169], v[118:121]
	v_mfma_f32_16x16x32_bf16 v[114:117], v[158:161], v[166:169], v[114:117]
	v_mfma_f32_16x16x32_bf16 v[102:105], v[150:153], v[174:177], v[102:105]
	v_mfma_f32_16x16x32_bf16 v[98:101], v[158:161], v[174:177], v[98:101]
	v_mfma_f32_16x16x32_bf16 v[84:87], v[150:153], v[232:235], v[84:87]
	v_mfma_f32_16x16x32_bf16 v[80:83], v[158:161], v[232:235], v[80:83]
	v_mfma_f32_16x16x32_bf16 v[68:71], v[150:153], v[246:249], v[68:71]
	v_mfma_f32_16x16x32_bf16 v[64:67], v[158:161], v[246:249], v[64:67]
	s_setprio 0
	s_barrier
; #define PG8_STAGE(bufoff, gbase, voff) do { _Pragma("unroll") for (int _i = 0; _i < 2; ++_i) \
;         __builtin_amdgcn_global_load_lds((const unsigned*)((const char*)(gbase) + (voff)[_i]), (PG8_LAS unsigned*)(lds + (bufoff) + ldsw + _i * 8192), 16, 0, 0); } while (0)
; #define PG8_LDA(dst, b, h) do { _Pragma("unroll") for (int m = 0; m < 4; ++m) _Pragma("unroll") for (int k = 0; k < 2; ++k) dst[m][k] = *(const PG8_LAS bf16x8*)(lds + PG8_SA(b, h) + aoff + m * 2048 + k * 1024); } while (0)
; #define PG8_MMA(ai, bj, At, Bt) do { __builtin_amdgcn_s_setprio(1); _Pragma("unroll") for (int m = 0; m < 4; ++m) _Pragma("unroll") for (int n = 0; n < 2; ++n) _Pragma("unroll") for (int k = 0; k < 2; ++k) \
;         acc[ai][bj][m][n] = __builtin_amdgcn_mfma_f32_16x16x32_bf16(Bt[n][k], At[m][k], acc[ai][bj][m][n], 0, 0, 0); __builtin_amdgcn_s_setprio(0); } while (0)
; #define PG8_WAIT_V(n) asm volatile("s_waitcnt vmcnt(" #n ")" ::: "memory")
; #define PG8_WAIT_L(n) asm volatile("s_waitcnt lgkmcnt(" #n ")" ::: "memory")
; #define PG8_BAR __builtin_amdgcn_s_barrier()
; #define PG8_SCHED __builtin_amdgcn_sched_barrier(0)
; template <class Epi, class Sched, bool ALIGN_EPI = false, bool SP2 = false>
; __device__ __forceinline__ void gemm_phase(PG8_LAS unsigned char* lds, const Gemm g, const Sched& S, const Epi& E) {
;     ...
;         for (int t = 0; t < nt; t += 2) {
;             const bool last = (t == nt - 2);
;             const char* a1 = cA + (size_t)(t + 1) * kstep;
;             const char* a2 = last ? nA : cA + (size_t)(t + 2) * kstep; const char* b2 = last ? nB : cB + (size_t)(t + 2) * kstep;
;     ...
;             PG8_LDA(At, 1, 1); PG8_STAGE(PG8_SB(1, 0), b3, voffB); PG8_STAGE(PG8_SB(1, 1), b3 + hstep, voffB); PG8_STAGE(PG8_SA(1, 0), a3, voffA);
;             PG8_WAIT_V(8); PG8_WAIT_L(0); PG8_BAR; PG8_MMA(1, 0, At, B0); PG8_MMA(1, 1, At, B1); PG8_BAR; PG8_SCHED;
	s_add_i32 s4, s30, s28
	v_lshl_add_u64 v[190:191], v[190:191], 0, s[20:21]
	s_mov_b32 m0, s4
	ds_read_b128 v[162:165], v209 offset:49152
	ds_read_b128 v[166:169], v209 offset:50176
	ds_read_b128 v[170:173], v209 offset:51200
	ds_read_b128 v[174:177], v209 offset:52224
	ds_read_b128 v[210:213], v209 offset:53248
	ds_read_b128 v[232:235], v209 offset:54272
	ds_read_b128 v[242:245], v209 offset:55296
	ds_read_b128 v[246:249], v209 offset:56320
	global_load_lds_dwordx4 v[190:191], off
	s_add_i32 m0, s4, 0x2000
	s_add_u32 s0, s0, 0x80080
	v_lshl_add_u64 v[190:191], v[204:205], 0, s[20:21]
	s_addc_u32 s1, s1, 0
	s_add_i32 s4, s31, s28
	global_load_lds_dwordx4 v[190:191], off
	v_lshl_add_u64 v[190:191], s[0:1], 0, v[96:97]
	s_mov_b32 m0, s4
	s_nop 0
	global_load_lds_dwordx4 v[190:191], off
	v_lshl_add_u64 v[190:191], s[0:1], 0, v[178:179]
	s_add_i32 m0, s4, 0x2000
	s_nop 0
	global_load_lds_dwordx4 v[190:191], off
	s_waitcnt vmcnt(6)
	s_waitcnt lgkmcnt(0)
	s_barrier
	s_setprio 1
	s_waitcnt lgkmcnt(0)
	v_mfma_f32_16x16x32_bf16 v[60:63], v[130:133], v[162:165], v[60:63]
	v_mfma_f32_16x16x32_bf16 v[56:59], v[138:141], v[162:165], v[56:59]
	v_mfma_f32_16x16x32_bf16 v[44:47], v[130:133], v[170:173], v[44:47]
	v_mfma_f32_16x16x32_bf16 v[40:43], v[138:141], v[170:173], v[40:43]
	v_lshl_add_u64 v[190:191], v[214:215], 0, s[20:21]
	s_mov_b32 m0, s74
	s_nop 0
	global_load_lds_dwordx4 v[190:191], off
	v_mfma_f32_16x16x32_bf16 v[28:31], v[130:133], v[210:213], v[28:31]
	v_mfma_f32_16x16x32_bf16 v[24:27], v[138:141], v[210:213], v[24:27]
	v_mfma_f32_16x16x32_bf16 v[12:15], v[130:133], v[242:245], v[12:15]
	v_mfma_f32_16x16x32_bf16 v[8:11], v[138:141], v[242:245], v[8:11]
	v_mfma_f32_16x16x32_bf16 v[60:63], v[134:137], v[166:169], v[60:63]
	v_mfma_f32_16x16x32_bf16 v[56:59], v[142:145], v[166:169], v[56:59]
	v_mfma_f32_16x16x32_bf16 v[44:47], v[134:137], v[174:177], v[44:47]
	v_mfma_f32_16x16x32_bf16 v[40:43], v[142:145], v[174:177], v[40:43]
	v_lshl_add_u64 v[190:191], v[228:229], 0, s[20:21]
	s_mov_b32 m0, s75
	s_nop 0
	global_load_lds_dwordx4 v[190:191], off
	v_mfma_f32_16x16x32_bf16 v[28:31], v[134:137], v[232:235], v[28:31]
	v_mfma_f32_16x16x32_bf16 v[24:27], v[142:145], v[232:235], v[24:27]
	v_mfma_f32_16x16x32_bf16 v[12:15], v[134:137], v[246:249], v[12:15]
	v_mfma_f32_16x16x32_bf16 v[8:11], v[142:145], v[246:249], v[8:11]
	s_setprio 0
	s_setprio 1
	v_mfma_f32_16x16x32_bf16 v[52:55], v[146:149], v[162:165], v[52:55]
	v_mfma_f32_16x16x32_bf16 v[48:51], v[154:157], v[162:165], v[48:51]
	v_mfma_f32_16x16x32_bf16 v[36:39], v[146:149], v[170:173], v[36:39]
	v_mfma_f32_16x16x32_bf16 v[32:35], v[154:157], v[170:173], v[32:35]
	v_mfma_f32_16x16x32_bf16 v[20:23], v[146:149], v[210:213], v[20:23]
	v_mfma_f32_16x16x32_bf16 v[16:19], v[154:157], v[210:213], v[16:19]
	v_mfma_f32_16x16x32_bf16 v[4:7], v[146:149], v[242:245], v[4:7]
	v_mfma_f32_16x16x32_bf16 v[0:3], v[154:157], v[242:245], v[0:3]
	v_mfma_f32_16x16x32_bf16 v[52:55], v[150:153], v[166:169], v[52:55]
	v_mfma_f32_16x16x32_bf16 v[48:51], v[158:161], v[166:169], v[48:51]
	v_mfma_f32_16x16x32_bf16 v[36:39], v[150:153], v[174:177], v[36:39]
	v_mfma_f32_16x16x32_bf16 v[32:35], v[158:161], v[174:177], v[32:35]
	v_mfma_f32_16x16x32_bf16 v[20:23], v[150:153], v[232:235], v[20:23]
	v_mfma_f32_16x16x32_bf16 v[16:19], v[158:161], v[232:235], v[16:19]
	v_mfma_f32_16x16x32_bf16 v[4:7], v[150:153], v[246:249], v[4:7]
	v_mfma_f32_16x16x32_bf16 v[0:3], v[158:161], v[246:249], v[0:3]
	s_setprio 0
	s_barrier
	s_add_i32 s19, s19, 2
	s_add_u32 s15, s15, 0x100
	s_addc_u32 s17, s17, 0
	s_add_u32 s40, s40, 0x100
	s_addc_u32 s41, s41, 0
	s_cmp_gt_u32 s19, 29
	s_cbranch_scc0 .LBB0_417
	s_and_b64 vcc, exec, s[34:35]
	s_cbranch_vccz .LBB0_420
	s_barrier

; #define PG8_STAGE(bufoff, gbase, voff) do { _Pragma("unroll") for (int _i = 0; _i < 2; ++_i) \
;         __builtin_amdgcn_global_load_lds((const unsigned*)((const char*)(gbase) + (voff)[_i]), (PG8_LAS unsigned*)(lds + (bufoff) + ldsw + _i * 8192), 16, 0, 0); } while (0)
; #define PG8_LDA(dst, b, h) do { _Pragma("unroll") for (int m = 0; m < 4; ++m) _Pragma("unroll") for (int k = 0; k < 2; ++k) dst[m][k] = *(const PG8_LAS bf16x8*)(lds + PG8_SA(b, h) + aoff + m * 2048 + k * 1024); } while (0)
; #define PG8_LDB(dst, b, h) do { _Pragma("unroll") for (int n = 0; n < 2; ++n) _Pragma("unroll") for (int k = 0; k < 2; ++k) dst[n][k] = *(const PG8_LAS bf16x8*)(lds + PG8_SB(b, h) + boff + n * 2048 + k * 1024); } while (0)
; #define PG8_MMA(ai, bj, At, Bt) do { __builtin_amdgcn_s_setprio(1); _Pragma("unroll") for (int m = 0; m < 4; ++m) _Pragma("unroll") for (int n = 0; n < 2; ++n) _Pragma("unroll") for (int k = 0; k < 2; ++k) \
;         acc[ai][bj][m][n] = __builtin_amdgcn_mfma_f32_16x16x32_bf16(Bt[n][k], At[m][k], acc[ai][bj][m][n], 0, 0, 0); __builtin_amdgcn_s_setprio(0); } while (0)
; #define PG8_WAIT_V(n) asm volatile("s_waitcnt vmcnt(" #n ")" ::: "memory")
; #define PG8_WAIT_L(n) asm volatile("s_waitcnt lgkmcnt(" #n ")" ::: "memory")
; #define PG8_BAR __builtin_amdgcn_s_barrier()
; #define PG8_SCHED __builtin_amdgcn_sched_barrier(0)
; template <class Epi, class Sched, bool ALIGN_EPI = false, bool SP2 = false>
; __device__ __forceinline__ void gemm_phase(PG8_LAS unsigned char* lds, const Gemm g, const Sched& S, const Epi& E) {
;     ...
;             PG8_LDB(B0, 0, 0); PG8_LDB(B1, 0, 1); PG8_SCHED; PG8_LDA(At, 0, 0); PG8_STAGE(PG8_SA(1, 1), a1 + hstep, voffA);
;             PG8_WAIT_V(8); PG8_WAIT_L(0); PG8_BAR; PG8_MMA(0, 0, At, B0); PG8_MMA(0, 1, At, B1); PG8_BAR; PG8_SCHED;
;             PG8_LDA(At, 0, 1); PG8_STAGE(PG8_SB(0, 0), b2, voffB); PG8_STAGE(PG8_SB(0, 1), b2 + hstep, voffB); PG8_STAGE(PG8_SA(0, 0), a2, voffA);
.LBB0_447:
	s_add_i32 s28, s0, 2
	s_add_u32 s30, s66, 0x80
	s_addc_u32 s1, s67, 0
	s_add_i32 s33, 0, 0x10000
	s_cmp_eq_u32 s59, s0
	s_cselect_b32 s1, s43, s1
	s_cselect_b32 s0, s42, s30
	s_cselect_b32 s31, s65, s23
	s_cselect_b32 s30, s64, s17
	s_add_i32 s52, 0, 0x14000
	v_add_u32_e32 v126, s33, v232
	v_add_u32_e32 v158, s52, v232
	ds_read_b128 v[98:101], v126
	ds_read_b128 v[106:109], v126 offset:1024
	ds_read_b128 v[118:121], v126 offset:2048
	ds_read_b128 v[126:129], v126 offset:3072
	ds_read_b128 v[138:141], v158
	ds_read_b128 v[142:145], v158 offset:1024
	ds_read_b128 v[150:153], v158 offset:2048
	ds_read_b128 v[158:161], v158 offset:3072
	v_lshl_add_u64 v[212:213], s[66:67], 0, v[210:211]
	s_add_i32 m0, s4, 0xc000
	ds_read_b128 v[162:165], v234
	ds_read_b128 v[166:169], v234 offset:1024
	ds_read_b128 v[170:173], v234 offset:2048
	ds_read_b128 v[174:177], v234 offset:3072
	ds_read_b128 v[178:181], v234 offset:4096
	ds_read_b128 v[182:185], v234 offset:5120
	ds_read_b128 v[186:189], v234 offset:6144
	ds_read_b128 v[190:193], v234 offset:7168
	global_load_lds_dwordx4 v[212:213], off
	v_lshl_add_u64 v[212:213], s[66:67], 0, v[208:209]
	s_add_i32 m0, s4, 0xe000
	s_nop 0
	global_load_lds_dwordx4 v[212:213], off
	s_waitcnt vmcnt(8)
	s_waitcnt lgkmcnt(0)
	s_barrier
	s_setprio 1
	s_waitcnt lgkmcnt(0)
	v_mfma_f32_16x16x32_bf16 v[154:157], v[98:101], v[162:165], v[154:157]
	v_mfma_f32_16x16x32_bf16 v[146:149], v[118:121], v[162:165], v[146:149]
	v_mfma_f32_16x16x32_bf16 v[122:125], v[98:101], v[170:173], v[122:125]
	v_mfma_f32_16x16x32_bf16 v[114:117], v[118:121], v[170:173], v[114:117]
	v_mfma_f32_16x16x32_bf16 v[92:95], v[98:101], v[178:181], v[92:95]
	v_mfma_f32_16x16x32_bf16 v[88:91], v[118:121], v[178:181], v[88:91]
	v_mfma_f32_16x16x32_bf16 v[76:79], v[98:101], v[186:189], v[76:79]
	v_mfma_f32_16x16x32_bf16 v[72:75], v[118:121], v[186:189], v[72:75]
	v_mfma_f32_16x16x32_bf16 v[154:157], v[106:109], v[166:169], v[154:157]
	v_mfma_f32_16x16x32_bf16 v[146:149], v[126:129], v[166:169], v[146:149]
	v_mfma_f32_16x16x32_bf16 v[122:125], v[106:109], v[174:177], v[122:125]
	v_mfma_f32_16x16x32_bf16 v[114:117], v[126:129], v[174:177], v[114:117]
	v_mfma_f32_16x16x32_bf16 v[92:95], v[106:109], v[182:185], v[92:95]
	v_mfma_f32_16x16x32_bf16 v[88:91], v[126:129], v[182:185], v[88:91]
	v_mfma_f32_16x16x32_bf16 v[76:79], v[106:109], v[190:193], v[76:79]
	v_mfma_f32_16x16x32_bf16 v[72:75], v[126:129], v[190:193], v[72:75]
	s_setprio 0
	s_setprio 1
	v_mfma_f32_16x16x32_bf16 v[134:137], v[138:141], v[162:165], v[134:137]
	v_mfma_f32_16x16x32_bf16 v[130:133], v[150:153], v[162:165], v[130:133]
	v_mfma_f32_16x16x32_bf16 v[110:113], v[138:141], v[170:173], v[110:113]
	v_mfma_f32_16x16x32_bf16 v[102:105], v[150:153], v[170:173], v[102:105]
	v_mfma_f32_16x16x32_bf16 v[84:87], v[138:141], v[178:181], v[84:87]
	v_mfma_f32_16x16x32_bf16 v[80:83], v[150:153], v[178:181], v[80:83]
	v_mfma_f32_16x16x32_bf16 v[68:71], v[138:141], v[186:189], v[68:71]
	v_mfma_f32_16x16x32_bf16 v[64:67], v[150:153], v[186:189], v[64:67]
	v_mfma_f32_16x16x32_bf16 v[134:137], v[142:145], v[166:169], v[134:137]
	v_mfma_f32_16x16x32_bf16 v[130:133], v[158:161], v[166:169], v[130:133]
	v_mfma_f32_16x16x32_bf16 v[110:113], v[142:145], v[174:177], v[110:113]
	v_mfma_f32_16x16x32_bf16 v[102:105], v[158:161], v[174:177], v[102:105]
	v_mfma_f32_16x16x32_bf16 v[84:87], v[142:145], v[182:185], v[84:87]
	v_mfma_f32_16x16x32_bf16 v[80:83], v[158:161], v[182:185], v[80:83]
	v_mfma_f32_16x16x32_bf16 v[68:71], v[142:145], v[190:193], v[68:71]
	v_mfma_f32_16x16x32_bf16 v[64:67], v[158:161], v[190:193], v[64:67]
	s_setprio 0
	s_barrier
	s_add_i32 s33, s33, s2
	v_lshl_add_u64 v[212:213], s[30:31], 0, v[96:97]
	s_mov_b32 m0, s33
	ds_read_b128 v[162:165], v234 offset:16384
	ds_read_b128 v[166:169], v234 offset:17408
	ds_read_b128 v[170:173], v234 offset:18432
	ds_read_b128 v[174:177], v234 offset:19456
	ds_read_b128 v[178:181], v234 offset:20480
	ds_read_b128 v[182:185], v234 offset:21504
	ds_read_b128 v[186:189], v234 offset:22528
	ds_read_b128 v[190:193], v234 offset:23552
	global_load_lds_dwordx4 v[212:213], off
	s_add_i32 m0, s33, 0x2000
	v_lshl_add_u64 v[214:215], s[30:31], 0, v[202:203]
	s_add_u32 s30, s30, s22
	s_addc_u32 s31, s31, 0
	s_add_i32 s33, s52, s2
	global_load_lds_dwordx4 v[214:215], off
	v_lshl_add_u64 v[228:229], s[30:31], 0, v[96:97]
	s_mov_b32 m0, s33
	v_lshl_add_u64 v[236:237], s[30:31], 0, v[202:203]
	global_load_lds_dwordx4 v[228:229], off
	s_add_i32 m0, s33, 0x2000
	v_lshl_add_u64 v[242:243], s[0:1], 0, v[206:207]
	global_load_lds_dwordx4 v[236:237], off
	s_waitcnt vmcnt(6)
	s_waitcnt lgkmcnt(0)
	s_barrier
; #define PG8_STAGE(bufoff, gbase, voff) do { _Pragma("unroll") for (int _i = 0; _i < 2; ++_i) \
;         __builtin_amdgcn_global_load_lds((const unsigned*)((const char*)(gbase) + (voff)[_i]), (PG8_LAS unsigned*)(lds + (bufoff) + ldsw + _i * 8192), 16, 0, 0); } while (0)
; #define PG8_LDA(dst, b, h) do { _Pragma("unroll") for (int m = 0; m < 4; ++m) _Pragma("unroll") for (int k = 0; k < 2; ++k) dst[m][k] = *(const PG8_LAS bf16x8*)(lds + PG8_SA(b, h) + aoff + m * 2048 + k * 1024); } while (0)
; #define PG8_LDB(dst, b, h) do { _Pragma("unroll") for (int n = 0; n < 2; ++n) _Pragma("unroll") for (int k = 0; k < 2; ++k) dst[n][k] = *(const PG8_LAS bf16x8*)(lds + PG8_SB(b, h) + boff + n * 2048 + k * 1024); } while (0)
; #define PG8_MMA(ai, bj, At, Bt) do { __builtin_amdgcn_s_setprio(1); _Pragma("unroll") for (int m = 0; m < 4; ++m) _Pragma("unroll") for (int n = 0; n < 2; ++n) _Pragma("unroll") for (int k = 0; k < 2; ++k) \
;         acc[ai][bj][m][n] = __builtin_amdgcn_mfma_f32_16x16x32_bf16(Bt[n][k], At[m][k], acc[ai][bj][m][n], 0, 0, 0); __builtin_amdgcn_s_setprio(0); } while (0)
; #define PG8_WAIT_V(n) asm volatile("s_waitcnt vmcnt(" #n ")" ::: "memory")
; #define PG8_WAIT_L(n) asm volatile("s_waitcnt lgkmcnt(" #n ")" ::: "memory")
; #define PG8_BAR __builtin_amdgcn_s_barrier()
; #define PG8_SCHED __builtin_amdgcn_sched_barrier(0)
; template <class Epi, class Sched, bool ALIGN_EPI = false, bool SP2 = false>
; __device__ __forceinline__ void gemm_phase(PG8_LAS unsigned char* lds, const Gemm g, const Sched& S, const Epi& E) {
;     ...
;             PG8_WAIT_V(8); PG8_WAIT_L(0); PG8_BAR; PG8_MMA(1, 0, At, B0); PG8_MMA(1, 1, At, B1); PG8_BAR; PG8_SCHED;
;             PG8_LDB(B0, 1, 0); PG8_LDB(B1, 1, 1); PG8_SCHED; PG8_LDA(At, 1, 0); PG8_STAGE(PG8_SA(0, 1), a2 + hstep, voffA);
;             PG8_WAIT_V(8); PG8_WAIT_L(0); PG8_BAR; PG8_MMA(0, 0, At, B0); PG8_MMA(0, 1, At, B1); PG8_BAR; PG8_SCHED;
	s_setprio 1
	s_waitcnt lgkmcnt(0)
	v_mfma_f32_16x16x32_bf16 v[60:63], v[98:101], v[162:165], v[60:63]
	v_mfma_f32_16x16x32_bf16 v[56:59], v[118:121], v[162:165], v[56:59]
	v_mfma_f32_16x16x32_bf16 v[44:47], v[98:101], v[170:173], v[44:47]
	v_mfma_f32_16x16x32_bf16 v[40:43], v[118:121], v[170:173], v[40:43]
	s_mov_b32 m0, s4
	v_lshl_add_u64 v[244:245], s[0:1], 0, v[204:205]
	global_load_lds_dwordx4 v[242:243], off
	v_mfma_f32_16x16x32_bf16 v[28:31], v[98:101], v[178:181], v[28:31]
	v_mfma_f32_16x16x32_bf16 v[24:27], v[118:121], v[178:181], v[24:27]
	v_mfma_f32_16x16x32_bf16 v[12:15], v[98:101], v[186:189], v[12:15]
	v_mfma_f32_16x16x32_bf16 v[8:11], v[118:121], v[186:189], v[8:11]
	v_mfma_f32_16x16x32_bf16 v[60:63], v[106:109], v[166:169], v[60:63]
	v_mfma_f32_16x16x32_bf16 v[56:59], v[126:129], v[166:169], v[56:59]
	v_mfma_f32_16x16x32_bf16 v[44:47], v[106:109], v[174:177], v[44:47]
	v_mfma_f32_16x16x32_bf16 v[40:43], v[126:129], v[174:177], v[40:43]
	s_mov_b32 m0, s5
	s_nop 0
	global_load_lds_dwordx4 v[244:245], off
	v_mfma_f32_16x16x32_bf16 v[28:31], v[106:109], v[182:185], v[28:31]
	v_mfma_f32_16x16x32_bf16 v[24:27], v[126:129], v[182:185], v[24:27]
	v_mfma_f32_16x16x32_bf16 v[12:15], v[106:109], v[190:193], v[12:15]
	v_mfma_f32_16x16x32_bf16 v[8:11], v[126:129], v[190:193], v[8:11]
	s_setprio 0
	s_setprio 1
	v_mfma_f32_16x16x32_bf16 v[52:55], v[138:141], v[162:165], v[52:55]
	v_mfma_f32_16x16x32_bf16 v[48:51], v[150:153], v[162:165], v[48:51]
	v_mfma_f32_16x16x32_bf16 v[36:39], v[138:141], v[170:173], v[36:39]
	v_mfma_f32_16x16x32_bf16 v[32:35], v[150:153], v[170:173], v[32:35]
	v_mfma_f32_16x16x32_bf16 v[20:23], v[138:141], v[178:181], v[20:23]
	v_mfma_f32_16x16x32_bf16 v[16:19], v[150:153], v[178:181], v[16:19]
	v_mfma_f32_16x16x32_bf16 v[4:7], v[138:141], v[186:189], v[4:7]
	v_mfma_f32_16x16x32_bf16 v[0:3], v[150:153], v[186:189], v[0:3]
	v_mfma_f32_16x16x32_bf16 v[52:55], v[142:145], v[166:169], v[52:55]
	v_mfma_f32_16x16x32_bf16 v[48:51], v[158:161], v[166:169], v[48:51]
	v_mfma_f32_16x16x32_bf16 v[36:39], v[142:145], v[174:177], v[36:39]
	v_mfma_f32_16x16x32_bf16 v[32:35], v[158:161], v[174:177], v[32:35]
	v_mfma_f32_16x16x32_bf16 v[20:23], v[142:145], v[182:185], v[20:23]
	v_mfma_f32_16x16x32_bf16 v[16:19], v[158:161], v[182:185], v[16:19]
	v_mfma_f32_16x16x32_bf16 v[4:7], v[142:145], v[190:193], v[4:7]
	v_mfma_f32_16x16x32_bf16 v[0:3], v[158:161], v[190:193], v[0:3]
	s_setprio 0
	s_barrier
	s_add_i32 s30, 0, 0x18000
	s_add_i32 s31, 0, 0x1c000
	v_add_u32_e32 v126, s30, v232
	v_add_u32_e32 v158, s31, v232
	ds_read_b128 v[98:101], v126
	ds_read_b128 v[106:109], v126 offset:1024
	ds_read_b128 v[118:121], v126 offset:2048
	ds_read_b128 v[126:129], v126 offset:3072
	ds_read_b128 v[138:141], v158
	ds_read_b128 v[142:145], v158 offset:1024
	ds_read_b128 v[150:153], v158 offset:2048
	ds_read_b128 v[158:161], v158 offset:3072
	s_add_u32 s0, s0, s22
	s_addc_u32 s1, s1, 0
	s_mov_b32 m0, s14
	v_lshl_add_u64 v[246:247], s[0:1], 0, v[206:207]
	ds_read_b128 v[162:165], v234 offset:32768
	ds_read_b128 v[166:169], v234 offset:33792
	ds_read_b128 v[170:173], v234 offset:34816
	ds_read_b128 v[174:177], v234 offset:35840
	ds_read_b128 v[178:181], v234 offset:36864
	ds_read_b128 v[182:185], v234 offset:37888
	ds_read_b128 v[186:189], v234 offset:38912
	ds_read_b128 v[190:193], v234 offset:39936
	global_load_lds_dwordx4 v[246:247], off
	v_lshl_add_u64 v[246:247], s[0:1], 0, v[204:205]
	s_mov_b32 m0, s15
	s_nop 0
	global_load_lds_dwordx4 v[246:247], off
	s_waitcnt vmcnt(8)
	s_waitcnt lgkmcnt(0)
	s_barrier
	s_setprio 1
	s_waitcnt lgkmcnt(0)
	v_mfma_f32_16x16x32_bf16 v[154:157], v[98:101], v[162:165], v[154:157]
	v_mfma_f32_16x16x32_bf16 v[146:149], v[118:121], v[162:165], v[146:149]
	v_mfma_f32_16x16x32_bf16 v[122:125], v[98:101], v[170:173], v[122:125]
	v_mfma_f32_16x16x32_bf16 v[114:117], v[118:121], v[170:173], v[114:117]
	v_mfma_f32_16x16x32_bf16 v[92:95], v[98:101], v[178:181], v[92:95]
	v_mfma_f32_16x16x32_bf16 v[88:91], v[118:121], v[178:181], v[88:91]
	v_mfma_f32_16x16x32_bf16 v[76:79], v[98:101], v[186:189], v[76:79]
	v_mfma_f32_16x16x32_bf16 v[72:75], v[118:121], v[186:189], v[72:75]
	v_mfma_f32_16x16x32_bf16 v[154:157], v[106:109], v[166:169], v[154:157]
	v_mfma_f32_16x16x32_bf16 v[146:149], v[126:129], v[166:169], v[146:149]
	v_mfma_f32_16x16x32_bf16 v[122:125], v[106:109], v[174:177], v[122:125]
	v_mfma_f32_16x16x32_bf16 v[114:117], v[126:129], v[174:177], v[114:117]
	v_mfma_f32_16x16x32_bf16 v[92:95], v[106:109], v[182:185], v[92:95]
	v_mfma_f32_16x16x32_bf16 v[88:91], v[126:129], v[182:185], v[88:91]
	v_mfma_f32_16x16x32_bf16 v[76:79], v[106:109], v[190:193], v[76:79]
	v_mfma_f32_16x16x32_bf16 v[72:75], v[126:129], v[190:193], v[72:75]
	s_setprio 0
	s_setprio 1
	v_mfma_f32_16x16x32_bf16 v[134:137], v[138:141], v[162:165], v[134:137]
	v_mfma_f32_16x16x32_bf16 v[130:133], v[150:153], v[162:165], v[130:133]
	v_mfma_f32_16x16x32_bf16 v[110:113], v[138:141], v[170:173], v[110:113]
	v_mfma_f32_16x16x32_bf16 v[102:105], v[150:153], v[170:173], v[102:105]
	v_mfma_f32_16x16x32_bf16 v[84:87], v[138:141], v[178:181], v[84:87]
	v_mfma_f32_16x16x32_bf16 v[80:83], v[150:153], v[178:181], v[80:83]
	v_mfma_f32_16x16x32_bf16 v[68:71], v[138:141], v[186:189], v[68:71]
	v_mfma_f32_16x16x32_bf16 v[64:67], v[150:153], v[186:189], v[64:67]
	v_mfma_f32_16x16x32_bf16 v[134:137], v[142:145], v[166:169], v[134:137]
	v_mfma_f32_16x16x32_bf16 v[130:133], v[158:161], v[166:169], v[130:133]
	v_mfma_f32_16x16x32_bf16 v[110:113], v[142:145], v[174:177], v[110:113]
	v_mfma_f32_16x16x32_bf16 v[102:105], v[158:161], v[174:177], v[102:105]
	v_mfma_f32_16x16x32_bf16 v[84:87], v[142:145], v[182:185], v[84:87]
	v_mfma_f32_16x16x32_bf16 v[80:83], v[158:161], v[182:185], v[80:83]
	v_mfma_f32_16x16x32_bf16 v[68:71], v[142:145], v[190:193], v[68:71]
	v_mfma_f32_16x16x32_bf16 v[64:67], v[158:161], v[190:193], v[64:67]
	s_setprio 0
	s_barrier
; #define PG8_STAGE(bufoff, gbase, voff) do { _Pragma("unroll") for (int _i = 0; _i < 2; ++_i) \
;         __builtin_amdgcn_global_load_lds((const unsigned*)((const char*)(gbase) + (voff)[_i]), (PG8_LAS unsigned*)(lds + (bufoff) + ldsw + _i * 8192), 16, 0, 0); } while (0)
; #define PG8_LDA(dst, b, h) do { _Pragma("unroll") for (int m = 0; m < 4; ++m) _Pragma("unroll") for (int k = 0; k < 2; ++k) dst[m][k] = *(const PG8_LAS bf16x8*)(lds + PG8_SA(b, h) + aoff + m * 2048 + k * 1024); } while (0)
; #define PG8_MMA(ai, bj, At, Bt) do { __builtin_amdgcn_s_setprio(1); _Pragma("unroll") for (int m = 0; m < 4; ++m) _Pragma("unroll") for (int n = 0; n < 2; ++n) _Pragma("unroll") for (int k = 0; k < 2; ++k) \
;         acc[ai][bj][m][n] = __builtin_amdgcn_mfma_f32_16x16x32_bf16(Bt[n][k], At[m][k], acc[ai][bj][m][n], 0, 0, 0); __builtin_amdgcn_s_setprio(0); } while (0)
; #define PG8_WAIT_V(n) asm volatile("s_waitcnt vmcnt(" #n ")" ::: "memory")
; #define PG8_WAIT_L(n) asm volatile("s_waitcnt lgkmcnt(" #n ")" ::: "memory")
; #define PG8_BAR __builtin_amdgcn_s_barrier()
; #define PG8_SCHED __builtin_amdgcn_sched_barrier(0)
; template <class Epi, class Sched, bool ALIGN_EPI = false, bool SP2 = false>
; __device__ __forceinline__ void gemm_phase(PG8_LAS unsigned char* lds, const Gemm g, const Sched& S, const Epi& E) {
;     ...
;         for (int t = 0; t < nt; t += 2) {
;             const bool last = (t == nt - 2);
;             const char* a1 = cA + (size_t)(t + 1) * kstep;
;             const char* a2 = last ? nA : cA + (size_t)(t + 2) * kstep; const char* b2 = last ? nB : cB + (size_t)(t + 2) * kstep;
;     ...
;             PG8_LDA(At, 1, 1); PG8_STAGE(PG8_SB(1, 0), b3, voffB); PG8_STAGE(PG8_SB(1, 1), b3 + hstep, voffB); PG8_STAGE(PG8_SA(1, 0), a3, voffA);
;             PG8_WAIT_V(8); PG8_WAIT_L(0); PG8_BAR; PG8_MMA(1, 0, At, B0); PG8_MMA(1, 1, At, B1); PG8_BAR; PG8_SCHED;
	s_add_i32 s0, s30, s2
	v_lshl_add_u64 v[212:213], v[212:213], 0, s[20:21]
	s_mov_b32 m0, s0
	ds_read_b128 v[162:165], v234 offset:49152
	ds_read_b128 v[166:169], v234 offset:50176
	ds_read_b128 v[170:173], v234 offset:51200
	ds_read_b128 v[174:177], v234 offset:52224
	ds_read_b128 v[178:181], v234 offset:53248
	ds_read_b128 v[182:185], v234 offset:54272
	ds_read_b128 v[186:189], v234 offset:55296
	ds_read_b128 v[190:193], v234 offset:56320
	global_load_lds_dwordx4 v[212:213], off
	v_lshl_add_u64 v[212:213], v[214:215], 0, s[20:21]
	s_add_i32 m0, s0, 0x2000
	s_add_i32 s0, s31, s2
	global_load_lds_dwordx4 v[212:213], off
	v_lshl_add_u64 v[212:213], v[228:229], 0, s[20:21]
	s_mov_b32 m0, s0
	s_nop 0
	global_load_lds_dwordx4 v[212:213], off
	v_lshl_add_u64 v[212:213], v[236:237], 0, s[20:21]
	s_add_i32 m0, s0, 0x2000
	s_nop 0
	global_load_lds_dwordx4 v[212:213], off
	s_waitcnt vmcnt(6)
	s_waitcnt lgkmcnt(0)
	s_barrier
	s_setprio 1
	s_waitcnt lgkmcnt(0)
	v_mfma_f32_16x16x32_bf16 v[60:63], v[98:101], v[162:165], v[60:63]
	v_mfma_f32_16x16x32_bf16 v[56:59], v[118:121], v[162:165], v[56:59]
	v_mfma_f32_16x16x32_bf16 v[44:47], v[98:101], v[170:173], v[44:47]
	v_mfma_f32_16x16x32_bf16 v[40:43], v[118:121], v[170:173], v[40:43]
	v_lshl_add_u64 v[212:213], v[242:243], 0, s[20:21]
	s_mov_b32 m0, s19
	s_nop 0
	global_load_lds_dwordx4 v[212:213], off
	v_mfma_f32_16x16x32_bf16 v[28:31], v[98:101], v[178:181], v[28:31]
	v_mfma_f32_16x16x32_bf16 v[24:27], v[118:121], v[178:181], v[24:27]
	v_mfma_f32_16x16x32_bf16 v[12:15], v[98:101], v[186:189], v[12:15]
	v_mfma_f32_16x16x32_bf16 v[8:11], v[118:121], v[186:189], v[8:11]
	v_mfma_f32_16x16x32_bf16 v[60:63], v[106:109], v[166:169], v[60:63]
	v_mfma_f32_16x16x32_bf16 v[56:59], v[126:129], v[166:169], v[56:59]
	v_mfma_f32_16x16x32_bf16 v[44:47], v[106:109], v[174:177], v[44:47]
	v_mfma_f32_16x16x32_bf16 v[40:43], v[126:129], v[174:177], v[40:43]
	v_lshl_add_u64 v[212:213], v[244:245], 0, s[20:21]
	s_mov_b32 m0, s46
	s_nop 0
	global_load_lds_dwordx4 v[212:213], off
	v_mfma_f32_16x16x32_bf16 v[28:31], v[106:109], v[182:185], v[28:31]
	v_mfma_f32_16x16x32_bf16 v[24:27], v[126:129], v[182:185], v[24:27]
	v_mfma_f32_16x16x32_bf16 v[12:15], v[106:109], v[190:193], v[12:15]
	v_mfma_f32_16x16x32_bf16 v[8:11], v[126:129], v[190:193], v[8:11]
	s_setprio 0
	s_setprio 1
	v_mfma_f32_16x16x32_bf16 v[52:55], v[138:141], v[162:165], v[52:55]
	v_mfma_f32_16x16x32_bf16 v[48:51], v[150:153], v[162:165], v[48:51]
	v_mfma_f32_16x16x32_bf16 v[36:39], v[138:141], v[170:173], v[36:39]
	v_mfma_f32_16x16x32_bf16 v[32:35], v[150:153], v[170:173], v[32:35]
	v_mfma_f32_16x16x32_bf16 v[20:23], v[138:141], v[178:181], v[20:23]
	v_mfma_f32_16x16x32_bf16 v[16:19], v[150:153], v[178:181], v[16:19]
	v_mfma_f32_16x16x32_bf16 v[4:7], v[138:141], v[186:189], v[4:7]
	v_mfma_f32_16x16x32_bf16 v[0:3], v[150:153], v[186:189], v[0:3]
	v_mfma_f32_16x16x32_bf16 v[52:55], v[142:145], v[166:169], v[52:55]
	v_mfma_f32_16x16x32_bf16 v[48:51], v[158:161], v[166:169], v[48:51]
	v_mfma_f32_16x16x32_bf16 v[36:39], v[142:145], v[174:177], v[36:39]
	v_mfma_f32_16x16x32_bf16 v[32:35], v[158:161], v[174:177], v[32:35]
	v_mfma_f32_16x16x32_bf16 v[20:23], v[142:145], v[182:185], v[20:23]
	v_mfma_f32_16x16x32_bf16 v[16:19], v[158:161], v[182:185], v[16:19]
	v_mfma_f32_16x16x32_bf16 v[4:7], v[142:145], v[190:193], v[4:7]
	v_mfma_f32_16x16x32_bf16 v[0:3], v[158:161], v[190:193], v[0:3]
	s_setprio 0
	s_barrier
	s_add_u32 s17, s17, 0x100
	s_addc_u32 s23, s23, 0
	s_add_u32 s66, s66, 0x100
	s_addc_u32 s67, s67, 0
	s_cmp_ge_u32 s28, s49
	s_mov_b32 s0, s28
	s_cbranch_scc0 .LBB0_447
	s_and_b64 vcc, exec, s[62:63]
	s_cbranch_vccz .LBB0_450
	s_barrier

; #define PG8_STAGE(bufoff, gbase, voff) do { _Pragma("unroll") for (int _i = 0; _i < 2; ++_i) \
;         __builtin_amdgcn_global_load_lds((const unsigned*)((const char*)(gbase) + (voff)[_i]), (PG8_LAS unsigned*)(lds + (bufoff) + ldsw + _i * 8192), 16, 0, 0); } while (0)
; #define PG8_LDA(dst, b, h) do { _Pragma("unroll") for (int m = 0; m < 4; ++m) _Pragma("unroll") for (int k = 0; k < 2; ++k) dst[m][k] = *(const PG8_LAS bf16x8*)(lds + PG8_SA(b, h) + aoff + m * 2048 + k * 1024); } while (0)
; #define PG8_LDB(dst, b, h) do { _Pragma("unroll") for (int n = 0; n < 2; ++n) _Pragma("unroll") for (int k = 0; k < 2; ++k) dst[n][k] = *(const PG8_LAS bf16x8*)(lds + PG8_SB(b, h) + boff + n * 2048 + k * 1024); } while (0)
; #define PG8_MMA(ai, bj, At, Bt) do { __builtin_amdgcn_s_setprio(1); _Pragma("unroll") for (int m = 0; m < 4; ++m) _Pragma("unroll") for (int n = 0; n < 2; ++n) _Pragma("unroll") for (int k = 0; k < 2; ++k) \
;         acc[ai][bj][m][n] = __builtin_amdgcn_mfma_f32_16x16x32_bf16(Bt[n][k], At[m][k], acc[ai][bj][m][n], 0, 0, 0); __builtin_amdgcn_s_setprio(0); } while (0)
; #define PG8_WAIT_V(n) asm volatile("s_waitcnt vmcnt(" #n ")" ::: "memory")
; #define PG8_WAIT_L(n) asm volatile("s_waitcnt lgkmcnt(" #n ")" ::: "memory")
; #define PG8_BAR __builtin_amdgcn_s_barrier()
; #define PG8_SCHED __builtin_amdgcn_sched_barrier(0)
; template <class Epi, class Sched, bool ALIGN_EPI = false, bool SP2 = false>
; __device__ __forceinline__ void gemm_phase(PG8_LAS unsigned char* lds, const Gemm g, const Sched& S, const Epi& E) {
;     ...
;             PG8_LDB(B0, 0, 0); PG8_LDB(B1, 0, 1); PG8_SCHED; PG8_LDA(At, 0, 0); PG8_STAGE(PG8_SA(1, 1), a1 + hstep, voffA);
;             PG8_WAIT_V(8); PG8_WAIT_L(0); PG8_BAR; PG8_MMA(0, 0, At, B0); PG8_MMA(0, 1, At, B1); PG8_BAR; PG8_SCHED;
;             PG8_LDA(At, 0, 1); PG8_STAGE(PG8_SB(0, 0), b2, voffB); PG8_STAGE(PG8_SB(0, 1), b2 + hstep, voffB); PG8_STAGE(PG8_SA(0, 0), a2, voffA);
.LBB0_510:
	s_add_i32 s95, s0, 2
	s_add_u32 s96, s40, 0x80
	s_addc_u32 s1, s41, 0
	s_add_i32 vcc_lo, 0, 0x10000
	s_cmp_eq_u32 s7, s0
	s_cselect_b32 s1, s89, s1
	s_cselect_b32 s0, s88, s96
	s_cselect_b32 s97, s87, s94
	s_cselect_b32 s96, s86, s45
	s_add_i32 vcc_hi, 0, 0x14000
	v_add_u32_e32 v142, vcc_lo, v193
	v_add_u32_e32 v158, vcc_hi, v193
	ds_read_b128 v[130:133], v142
	ds_read_b128 v[134:137], v142 offset:1024
	ds_read_b128 v[138:141], v142 offset:2048
	ds_read_b128 v[142:145], v142 offset:3072
	ds_read_b128 v[146:149], v158
	ds_read_b128 v[150:153], v158 offset:1024
	ds_read_b128 v[154:157], v158 offset:2048
	ds_read_b128 v[158:161], v158 offset:3072
	v_lshl_add_u64 v[202:203], s[40:41], 0, v[188:189]
	s_add_i32 m0, s90, 0xc000
	ds_read_b128 v[162:165], v207
	ds_read_b128 v[166:169], v207 offset:1024
	ds_read_b128 v[170:173], v207 offset:2048
	ds_read_b128 v[174:177], v207 offset:3072
	ds_read_b128 v[208:211], v207 offset:4096
	ds_read_b128 v[212:215], v207 offset:5120
	ds_read_b128 v[232:235], v207 offset:6144
	ds_read_b128 v[242:245], v207 offset:7168
	global_load_lds_dwordx4 v[202:203], off
	v_lshl_add_u64 v[202:203], s[40:41], 0, v[186:187]
	s_add_i32 m0, s90, 0xe000
	s_nop 0
	global_load_lds_dwordx4 v[202:203], off
	s_waitcnt vmcnt(8)
	s_waitcnt lgkmcnt(0)
	s_barrier
	s_setprio 1
	s_waitcnt lgkmcnt(0)
	v_mfma_f32_16x16x32_bf16 v[126:129], v[130:133], v[162:165], v[126:129]
	v_mfma_f32_16x16x32_bf16 v[122:125], v[138:141], v[162:165], v[122:125]
	v_mfma_f32_16x16x32_bf16 v[114:117], v[130:133], v[170:173], v[114:117]
	v_mfma_f32_16x16x32_bf16 v[106:109], v[138:141], v[170:173], v[106:109]
	v_mfma_f32_16x16x32_bf16 v[98:101], v[130:133], v[208:211], v[98:101]
	v_mfma_f32_16x16x32_bf16 v[88:91], v[138:141], v[208:211], v[88:91]
	v_mfma_f32_16x16x32_bf16 v[80:83], v[130:133], v[232:235], v[80:83]
	v_mfma_f32_16x16x32_bf16 v[72:75], v[138:141], v[232:235], v[72:75]
	v_mfma_f32_16x16x32_bf16 v[126:129], v[134:137], v[166:169], v[126:129]
	v_mfma_f32_16x16x32_bf16 v[122:125], v[142:145], v[166:169], v[122:125]
	v_mfma_f32_16x16x32_bf16 v[114:117], v[134:137], v[174:177], v[114:117]
	v_mfma_f32_16x16x32_bf16 v[106:109], v[142:145], v[174:177], v[106:109]
	v_mfma_f32_16x16x32_bf16 v[98:101], v[134:137], v[212:215], v[98:101]
	v_mfma_f32_16x16x32_bf16 v[88:91], v[142:145], v[212:215], v[88:91]
	v_mfma_f32_16x16x32_bf16 v[80:83], v[134:137], v[242:245], v[80:83]
	v_mfma_f32_16x16x32_bf16 v[72:75], v[142:145], v[242:245], v[72:75]
	s_setprio 0
	s_setprio 1
	v_mfma_f32_16x16x32_bf16 v[118:121], v[146:149], v[162:165], v[118:121]
	v_mfma_f32_16x16x32_bf16 v[110:113], v[154:157], v[162:165], v[110:113]
	v_mfma_f32_16x16x32_bf16 v[102:105], v[146:149], v[170:173], v[102:105]
	v_mfma_f32_16x16x32_bf16 v[92:95], v[154:157], v[170:173], v[92:95]
	v_mfma_f32_16x16x32_bf16 v[84:87], v[146:149], v[208:211], v[84:87]
	v_mfma_f32_16x16x32_bf16 v[76:79], v[154:157], v[208:211], v[76:79]
	v_mfma_f32_16x16x32_bf16 v[68:71], v[146:149], v[232:235], v[68:71]
	v_mfma_f32_16x16x32_bf16 v[64:67], v[154:157], v[232:235], v[64:67]
	v_mfma_f32_16x16x32_bf16 v[118:121], v[150:153], v[166:169], v[118:121]
	v_mfma_f32_16x16x32_bf16 v[110:113], v[158:161], v[166:169], v[110:113]
	v_mfma_f32_16x16x32_bf16 v[102:105], v[150:153], v[174:177], v[102:105]
	v_mfma_f32_16x16x32_bf16 v[92:95], v[158:161], v[174:177], v[92:95]
	v_mfma_f32_16x16x32_bf16 v[84:87], v[150:153], v[212:215], v[84:87]
	v_mfma_f32_16x16x32_bf16 v[76:79], v[158:161], v[212:215], v[76:79]
	v_mfma_f32_16x16x32_bf16 v[68:71], v[150:153], v[242:245], v[68:71]
	v_mfma_f32_16x16x32_bf16 v[64:67], v[158:161], v[242:245], v[64:67]
	s_setprio 0
	s_barrier
	s_add_i32 vcc_lo, vcc_lo, s4
	v_lshl_add_u64 v[202:203], s[96:97], 0, v[96:97]
	s_mov_b32 m0, vcc_lo
	ds_read_b128 v[162:165], v207 offset:16384
	ds_read_b128 v[166:169], v207 offset:17408
	ds_read_b128 v[170:173], v207 offset:18432
	ds_read_b128 v[174:177], v207 offset:19456
	ds_read_b128 v[208:211], v207 offset:20480
	ds_read_b128 v[212:215], v207 offset:21504
	ds_read_b128 v[232:235], v207 offset:22528
	ds_read_b128 v[242:245], v207 offset:23552
	global_load_lds_dwordx4 v[202:203], off
	s_add_i32 m0, vcc_lo, 0x2000
	v_lshl_add_u64 v[228:229], s[96:97], 0, v[178:179]
	s_add_u32 s96, s96, s28
	s_addc_u32 s97, s97, 0
	s_add_i32 vcc_lo, vcc_hi, s4
	global_load_lds_dwordx4 v[228:229], off
	v_lshl_add_u64 v[230:231], s[96:97], 0, v[96:97]
	s_mov_b32 m0, vcc_lo
	v_lshl_add_u64 v[246:247], s[96:97], 0, v[178:179]
	global_load_lds_dwordx4 v[230:231], off
	s_add_i32 m0, vcc_lo, 0x2000
	v_lshl_add_u64 v[248:249], s[0:1], 0, v[182:183]
	global_load_lds_dwordx4 v[246:247], off
	s_waitcnt vmcnt(6)
	s_waitcnt lgkmcnt(0)
	s_barrier
; #define PG8_STAGE(bufoff, gbase, voff) do { _Pragma("unroll") for (int _i = 0; _i < 2; ++_i) \
;         __builtin_amdgcn_global_load_lds((const unsigned*)((const char*)(gbase) + (voff)[_i]), (PG8_LAS unsigned*)(lds + (bufoff) + ldsw + _i * 8192), 16, 0, 0); } while (0)
; #define PG8_LDA(dst, b, h) do { _Pragma("unroll") for (int m = 0; m < 4; ++m) _Pragma("unroll") for (int k = 0; k < 2; ++k) dst[m][k] = *(const PG8_LAS bf16x8*)(lds + PG8_SA(b, h) + aoff + m * 2048 + k * 1024); } while (0)
; #define PG8_LDB(dst, b, h) do { _Pragma("unroll") for (int n = 0; n < 2; ++n) _Pragma("unroll") for (int k = 0; k < 2; ++k) dst[n][k] = *(const PG8_LAS bf16x8*)(lds + PG8_SB(b, h) + boff + n * 2048 + k * 1024); } while (0)
; #define PG8_MMA(ai, bj, At, Bt) do { __builtin_amdgcn_s_setprio(1); _Pragma("unroll") for (int m = 0; m < 4; ++m) _Pragma("unroll") for (int n = 0; n < 2; ++n) _Pragma("unroll") for (int k = 0; k < 2; ++k) \
;         acc[ai][bj][m][n] = __builtin_amdgcn_mfma_f32_16x16x32_bf16(Bt[n][k], At[m][k], acc[ai][bj][m][n], 0, 0, 0); __builtin_amdgcn_s_setprio(0); } while (0)
; #define PG8_WAIT_V(n) asm volatile("s_waitcnt vmcnt(" #n ")" ::: "memory")
; #define PG8_WAIT_L(n) asm volatile("s_waitcnt lgkmcnt(" #n ")" ::: "memory")
; #define PG8_BAR __builtin_amdgcn_s_barrier()
; #define PG8_SCHED __builtin_amdgcn_sched_barrier(0)
; template <class Epi, class Sched, bool ALIGN_EPI = false, bool SP2 = false>
; __device__ __forceinline__ void gemm_phase(PG8_LAS unsigned char* lds, const Gemm g, const Sched& S, const Epi& E) {
;     ...
;             PG8_WAIT_V(8); PG8_WAIT_L(0); PG8_BAR; PG8_MMA(1, 0, At, B0); PG8_MMA(1, 1, At, B1); PG8_BAR; PG8_SCHED;
;             PG8_LDB(B0, 1, 0); PG8_LDB(B1, 1, 1); PG8_SCHED; PG8_LDA(At, 1, 0); PG8_STAGE(PG8_SA(0, 1), a2 + hstep, voffA);
;             PG8_WAIT_V(8); PG8_WAIT_L(0); PG8_BAR; PG8_MMA(0, 0, At, B0); PG8_MMA(0, 1, At, B1); PG8_BAR; PG8_SCHED;
	s_setprio 1
	s_waitcnt lgkmcnt(0)
	v_mfma_f32_16x16x32_bf16 v[60:63], v[130:133], v[162:165], v[60:63]
	v_mfma_f32_16x16x32_bf16 v[56:59], v[138:141], v[162:165], v[56:59]
	v_mfma_f32_16x16x32_bf16 v[48:51], v[130:133], v[170:173], v[48:51]
	v_mfma_f32_16x16x32_bf16 v[40:43], v[138:141], v[170:173], v[40:43]
	s_mov_b32 m0, s90
	v_lshl_add_u64 v[236:237], s[0:1], 0, v[180:181]
	global_load_lds_dwordx4 v[248:249], off
	v_mfma_f32_16x16x32_bf16 v[32:35], v[130:133], v[208:211], v[32:35]
	v_mfma_f32_16x16x32_bf16 v[24:27], v[138:141], v[208:211], v[24:27]
	v_mfma_f32_16x16x32_bf16 v[16:19], v[130:133], v[232:235], v[16:19]
	v_mfma_f32_16x16x32_bf16 v[8:11], v[138:141], v[232:235], v[8:11]
	v_mfma_f32_16x16x32_bf16 v[60:63], v[134:137], v[166:169], v[60:63]
	v_mfma_f32_16x16x32_bf16 v[56:59], v[142:145], v[166:169], v[56:59]
	v_mfma_f32_16x16x32_bf16 v[48:51], v[134:137], v[174:177], v[48:51]
	v_mfma_f32_16x16x32_bf16 v[40:43], v[142:145], v[174:177], v[40:43]
	s_mov_b32 m0, s8
	s_nop 0
	global_load_lds_dwordx4 v[236:237], off
	v_mfma_f32_16x16x32_bf16 v[32:35], v[134:137], v[212:215], v[32:35]
	v_mfma_f32_16x16x32_bf16 v[24:27], v[142:145], v[212:215], v[24:27]
	v_mfma_f32_16x16x32_bf16 v[16:19], v[134:137], v[242:245], v[16:19]
	v_mfma_f32_16x16x32_bf16 v[8:11], v[142:145], v[242:245], v[8:11]
	s_setprio 0
	s_setprio 1
	v_mfma_f32_16x16x32_bf16 v[52:55], v[146:149], v[162:165], v[52:55]
	v_mfma_f32_16x16x32_bf16 v[44:47], v[154:157], v[162:165], v[44:47]
	v_mfma_f32_16x16x32_bf16 v[36:39], v[146:149], v[170:173], v[36:39]
	v_mfma_f32_16x16x32_bf16 v[28:31], v[154:157], v[170:173], v[28:31]
	v_mfma_f32_16x16x32_bf16 v[20:23], v[146:149], v[208:211], v[20:23]
	v_mfma_f32_16x16x32_bf16 v[12:15], v[154:157], v[208:211], v[12:15]
	v_mfma_f32_16x16x32_bf16 v[4:7], v[146:149], v[232:235], v[4:7]
	v_mfma_f32_16x16x32_bf16 v[0:3], v[154:157], v[232:235], v[0:3]
	v_mfma_f32_16x16x32_bf16 v[52:55], v[150:153], v[166:169], v[52:55]
	v_mfma_f32_16x16x32_bf16 v[44:47], v[158:161], v[166:169], v[44:47]
	v_mfma_f32_16x16x32_bf16 v[36:39], v[150:153], v[174:177], v[36:39]
	v_mfma_f32_16x16x32_bf16 v[28:31], v[158:161], v[174:177], v[28:31]
	v_mfma_f32_16x16x32_bf16 v[20:23], v[150:153], v[212:215], v[20:23]
	v_mfma_f32_16x16x32_bf16 v[12:15], v[158:161], v[212:215], v[12:15]
	v_mfma_f32_16x16x32_bf16 v[4:7], v[150:153], v[242:245], v[4:7]
	v_mfma_f32_16x16x32_bf16 v[0:3], v[158:161], v[242:245], v[0:3]
	s_setprio 0
	s_barrier
	s_add_i32 s96, 0, 0x18000
	s_add_i32 s97, 0, 0x1c000
	v_add_u32_e32 v142, s96, v193
	v_add_u32_e32 v158, s97, v193
	ds_read_b128 v[130:133], v142
	ds_read_b128 v[134:137], v142 offset:1024
	ds_read_b128 v[138:141], v142 offset:2048
	ds_read_b128 v[142:145], v142 offset:3072
	ds_read_b128 v[146:149], v158
	ds_read_b128 v[150:153], v158 offset:1024
	ds_read_b128 v[154:157], v158 offset:2048
	ds_read_b128 v[158:161], v158 offset:3072
	s_add_u32 s0, s0, s28
	s_addc_u32 s1, s1, 0
	s_mov_b32 m0, s9
	v_lshl_add_u64 v[250:251], s[0:1], 0, v[182:183]
	ds_read_b128 v[162:165], v207 offset:32768
	ds_read_b128 v[166:169], v207 offset:33792
	ds_read_b128 v[170:173], v207 offset:34816
	ds_read_b128 v[174:177], v207 offset:35840
	ds_read_b128 v[208:211], v207 offset:36864
	ds_read_b128 v[212:215], v207 offset:37888
	ds_read_b128 v[232:235], v207 offset:38912
	ds_read_b128 v[242:245], v207 offset:39936
	global_load_lds_dwordx4 v[250:251], off
	v_lshl_add_u64 v[250:251], s[0:1], 0, v[180:181]
	s_mov_b32 m0, s33
	s_nop 0
	global_load_lds_dwordx4 v[250:251], off
	s_waitcnt vmcnt(8)
	s_waitcnt lgkmcnt(0)
	s_barrier
	s_setprio 1
	s_waitcnt lgkmcnt(0)
	v_mfma_f32_16x16x32_bf16 v[126:129], v[130:133], v[162:165], v[126:129]
	v_mfma_f32_16x16x32_bf16 v[122:125], v[138:141], v[162:165], v[122:125]
	v_mfma_f32_16x16x32_bf16 v[114:117], v[130:133], v[170:173], v[114:117]
	v_mfma_f32_16x16x32_bf16 v[106:109], v[138:141], v[170:173], v[106:109]
	v_mfma_f32_16x16x32_bf16 v[98:101], v[130:133], v[208:211], v[98:101]
	v_mfma_f32_16x16x32_bf16 v[88:91], v[138:141], v[208:211], v[88:91]
	v_mfma_f32_16x16x32_bf16 v[80:83], v[130:133], v[232:235], v[80:83]
	v_mfma_f32_16x16x32_bf16 v[72:75], v[138:141], v[232:235], v[72:75]
	v_mfma_f32_16x16x32_bf16 v[126:129], v[134:137], v[166:169], v[126:129]
	v_mfma_f32_16x16x32_bf16 v[122:125], v[142:145], v[166:169], v[122:125]
	v_mfma_f32_16x16x32_bf16 v[114:117], v[134:137], v[174:177], v[114:117]
	v_mfma_f32_16x16x32_bf16 v[106:109], v[142:145], v[174:177], v[106:109]
	v_mfma_f32_16x16x32_bf16 v[98:101], v[134:137], v[212:215], v[98:101]
	v_mfma_f32_16x16x32_bf16 v[88:91], v[142:145], v[212:215], v[88:91]
	v_mfma_f32_16x16x32_bf16 v[80:83], v[134:137], v[242:245], v[80:83]
	v_mfma_f32_16x16x32_bf16 v[72:75], v[142:145], v[242:245], v[72:75]
	s_setprio 0
	s_setprio 1
	v_mfma_f32_16x16x32_bf16 v[118:121], v[146:149], v[162:165], v[118:121]
	v_mfma_f32_16x16x32_bf16 v[110:113], v[154:157], v[162:165], v[110:113]
	v_mfma_f32_16x16x32_bf16 v[102:105], v[146:149], v[170:173], v[102:105]
	v_mfma_f32_16x16x32_bf16 v[92:95], v[154:157], v[170:173], v[92:95]
	v_mfma_f32_16x16x32_bf16 v[84:87], v[146:149], v[208:211], v[84:87]
	v_mfma_f32_16x16x32_bf16 v[76:79], v[154:157], v[208:211], v[76:79]
	v_mfma_f32_16x16x32_bf16 v[68:71], v[146:149], v[232:235], v[68:71]
	v_mfma_f32_16x16x32_bf16 v[64:67], v[154:157], v[232:235], v[64:67]
	v_mfma_f32_16x16x32_bf16 v[118:121], v[150:153], v[166:169], v[118:121]
	v_mfma_f32_16x16x32_bf16 v[110:113], v[158:161], v[166:169], v[110:113]
	v_mfma_f32_16x16x32_bf16 v[102:105], v[150:153], v[174:177], v[102:105]
	v_mfma_f32_16x16x32_bf16 v[92:95], v[158:161], v[174:177], v[92:95]
	v_mfma_f32_16x16x32_bf16 v[84:87], v[150:153], v[212:215], v[84:87]
	v_mfma_f32_16x16x32_bf16 v[76:79], v[158:161], v[212:215], v[76:79]
	v_mfma_f32_16x16x32_bf16 v[68:71], v[150:153], v[242:245], v[68:71]
	v_mfma_f32_16x16x32_bf16 v[64:67], v[158:161], v[242:245], v[64:67]
	s_setprio 0
	s_barrier
; #define PG8_STAGE(bufoff, gbase, voff) do { _Pragma("unroll") for (int _i = 0; _i < 2; ++_i) \
;         __builtin_amdgcn_global_load_lds((const unsigned*)((const char*)(gbase) + (voff)[_i]), (PG8_LAS unsigned*)(lds + (bufoff) + ldsw + _i * 8192), 16, 0, 0); } while (0)
; #define PG8_LDA(dst, b, h) do { _Pragma("unroll") for (int m = 0; m < 4; ++m) _Pragma("unroll") for (int k = 0; k < 2; ++k) dst[m][k] = *(const PG8_LAS bf16x8*)(lds + PG8_SA(b, h) + aoff + m * 2048 + k * 1024); } while (0)
; #define PG8_MMA(ai, bj, At, Bt) do { __builtin_amdgcn_s_setprio(1); _Pragma("unroll") for (int m = 0; m < 4; ++m) _Pragma("unroll") for (int n = 0; n < 2; ++n) _Pragma("unroll") for (int k = 0; k < 2; ++k) \
;         acc[ai][bj][m][n] = __builtin_amdgcn_mfma_f32_16x16x32_bf16(Bt[n][k], At[m][k], acc[ai][bj][m][n], 0, 0, 0); __builtin_amdgcn_s_setprio(0); } while (0)
; #define PG8_WAIT_V(n) asm volatile("s_waitcnt vmcnt(" #n ")" ::: "memory")
; #define PG8_WAIT_L(n) asm volatile("s_waitcnt lgkmcnt(" #n ")" ::: "memory")
; #define PG8_BAR __builtin_amdgcn_s_barrier()
; #define PG8_SCHED __builtin_amdgcn_sched_barrier(0)
; template <class Epi, class Sched, bool ALIGN_EPI = false, bool SP2 = false>
; __device__ __forceinline__ void gemm_phase(PG8_LAS unsigned char* lds, const Gemm g, const Sched& S, const Epi& E) {
;     ...
;         for (int t = 0; t < nt; t += 2) {
;             const bool last = (t == nt - 2);
;             const char* a1 = cA + (size_t)(t + 1) * kstep;
;             const char* a2 = last ? nA : cA + (size_t)(t + 2) * kstep; const char* b2 = last ? nB : cB + (size_t)(t + 2) * kstep;
;     ...
;             PG8_LDA(At, 1, 1); PG8_STAGE(PG8_SB(1, 0), b3, voffB); PG8_STAGE(PG8_SB(1, 1), b3 + hstep, voffB); PG8_STAGE(PG8_SA(1, 0), a3, voffA);
;             PG8_WAIT_V(8); PG8_WAIT_L(0); PG8_BAR; PG8_MMA(1, 0, At, B0); PG8_MMA(1, 1, At, B1); PG8_BAR; PG8_SCHED;
	s_add_i32 s0, s96, s4
	v_lshl_add_u64 v[202:203], v[202:203], 0, s[20:21]
	s_mov_b32 m0, s0
	ds_read_b128 v[162:165], v207 offset:49152
	ds_read_b128 v[166:169], v207 offset:50176
	ds_read_b128 v[170:173], v207 offset:51200
	ds_read_b128 v[174:177], v207 offset:52224
	ds_read_b128 v[208:211], v207 offset:53248
	ds_read_b128 v[212:215], v207 offset:54272
	ds_read_b128 v[232:235], v207 offset:55296
	ds_read_b128 v[242:245], v207 offset:56320
	global_load_lds_dwordx4 v[202:203], off
	v_lshl_add_u64 v[202:203], v[228:229], 0, s[20:21]
	s_add_i32 m0, s0, 0x2000
	s_add_i32 s0, s97, s4
	global_load_lds_dwordx4 v[202:203], off
	v_lshl_add_u64 v[202:203], v[230:231], 0, s[20:21]
	s_mov_b32 m0, s0
	s_nop 0
	global_load_lds_dwordx4 v[202:203], off
	v_lshl_add_u64 v[202:203], v[246:247], 0, s[20:21]
	s_add_i32 m0, s0, 0x2000
	s_nop 0
	global_load_lds_dwordx4 v[202:203], off
	s_waitcnt vmcnt(6)
	s_waitcnt lgkmcnt(0)
	s_barrier
	s_setprio 1
	s_waitcnt lgkmcnt(0)
	v_mfma_f32_16x16x32_bf16 v[60:63], v[130:133], v[162:165], v[60:63]
	v_mfma_f32_16x16x32_bf16 v[56:59], v[138:141], v[162:165], v[56:59]
	v_mfma_f32_16x16x32_bf16 v[48:51], v[130:133], v[170:173], v[48:51]
	v_mfma_f32_16x16x32_bf16 v[40:43], v[138:141], v[170:173], v[40:43]
	v_lshl_add_u64 v[202:203], v[248:249], 0, s[20:21]
	s_mov_b32 m0, s53
	s_nop 0
	global_load_lds_dwordx4 v[202:203], off
	v_mfma_f32_16x16x32_bf16 v[32:35], v[130:133], v[208:211], v[32:35]
	v_mfma_f32_16x16x32_bf16 v[24:27], v[138:141], v[208:211], v[24:27]
	v_mfma_f32_16x16x32_bf16 v[16:19], v[130:133], v[232:235], v[16:19]
	v_mfma_f32_16x16x32_bf16 v[8:11], v[138:141], v[232:235], v[8:11]
	v_mfma_f32_16x16x32_bf16 v[60:63], v[134:137], v[166:169], v[60:63]
	v_mfma_f32_16x16x32_bf16 v[56:59], v[142:145], v[166:169], v[56:59]
	v_mfma_f32_16x16x32_bf16 v[48:51], v[134:137], v[174:177], v[48:51]
	v_mfma_f32_16x16x32_bf16 v[40:43], v[142:145], v[174:177], v[40:43]
	v_lshl_add_u64 v[202:203], v[236:237], 0, s[20:21]
	s_mov_b32 m0, s93
	s_nop 0
	global_load_lds_dwordx4 v[202:203], off
	v_mfma_f32_16x16x32_bf16 v[32:35], v[134:137], v[212:215], v[32:35]
	v_mfma_f32_16x16x32_bf16 v[24:27], v[142:145], v[212:215], v[24:27]
	v_mfma_f32_16x16x32_bf16 v[16:19], v[134:137], v[242:245], v[16:19]
	v_mfma_f32_16x16x32_bf16 v[8:11], v[142:145], v[242:245], v[8:11]
	s_setprio 0
	s_setprio 1
	v_mfma_f32_16x16x32_bf16 v[52:55], v[146:149], v[162:165], v[52:55]
	v_mfma_f32_16x16x32_bf16 v[44:47], v[154:157], v[162:165], v[44:47]
	v_mfma_f32_16x16x32_bf16 v[36:39], v[146:149], v[170:173], v[36:39]
	v_mfma_f32_16x16x32_bf16 v[28:31], v[154:157], v[170:173], v[28:31]
	v_mfma_f32_16x16x32_bf16 v[20:23], v[146:149], v[208:211], v[20:23]
	v_mfma_f32_16x16x32_bf16 v[12:15], v[154:157], v[208:211], v[12:15]
	v_mfma_f32_16x16x32_bf16 v[4:7], v[146:149], v[232:235], v[4:7]
	v_mfma_f32_16x16x32_bf16 v[0:3], v[154:157], v[232:235], v[0:3]
	v_mfma_f32_16x16x32_bf16 v[52:55], v[150:153], v[166:169], v[52:55]
	v_mfma_f32_16x16x32_bf16 v[44:47], v[158:161], v[166:169], v[44:47]
	v_mfma_f32_16x16x32_bf16 v[36:39], v[150:153], v[174:177], v[36:39]
	v_mfma_f32_16x16x32_bf16 v[28:31], v[158:161], v[174:177], v[28:31]
	v_mfma_f32_16x16x32_bf16 v[20:23], v[150:153], v[212:215], v[20:23]
	v_mfma_f32_16x16x32_bf16 v[12:15], v[158:161], v[212:215], v[12:15]
	v_mfma_f32_16x16x32_bf16 v[4:7], v[150:153], v[242:245], v[4:7]
	v_mfma_f32_16x16x32_bf16 v[0:3], v[158:161], v[242:245], v[0:3]
	s_setprio 0
	s_barrier
	s_add_u32 s45, s45, 0x100
	s_addc_u32 s94, s94, 0
	s_add_u32 s40, s40, 0x100
	s_addc_u32 s41, s41, 0
	s_cmp_ge_u32 s95, s58
	s_mov_b32 s0, s95
	s_cbranch_scc0 .LBB0_510
	s_and_b64 vcc, exec, s[82:83]
	s_cbranch_vccz .LBB0_513
	s_barrier
